# phase C copy-out: left-over items moved from the three-pass workgroups to the sample-chain workgroups
# baseline (speedup 1.0000x reference)
.LBB0_111:
	s_andn2_b64 vcc, exec, s[0:1]
	s_cbranch_vccnz .LBB0_380
	s_mov_b64 s[0:1], s[36:37]
	s_waitcnt vmcnt(0)
	v_mov_b32_e32 v0, v224
	v_readlane_b32 s2, v253, 0
	s_nop 1
	v_lshl_add_u32 v2, s2, 9, v0
	s_mov_b32 s2, 0x24000
	v_cmp_gt_i32_e32 vcc, s2, v2
	s_and_saveexec_b64 s[2:3], vcc
	s_cbranch_execz .LBB0_120
	v_readlane_b32 s38, v253, 0
	s_and_b32 s39, s38, 0xffffff87
	s_cmp_eq_u32 s39, 0
	s_cbranch_scc1 .Lcpre_chain
	s_mov_b32 s38, 0x100000
	s_mov_b32 s39, 0x23fff
	s_branch .Lcpre_set
.Lcpre_chain:
	s_lshr_b32 s39, s38, 3
	s_lshl_b32 s39, s39, 10
	s_add_i32 s39, s39, 0x20000
	s_lshl_b32 s38, s38, 9
	s_sub_i32 s38, s39, s38
	s_add_i32 s39, s39, 0x3ff
.Lcpre_set:
	v_readlane_b32 s4, v254, 21
	s_lshl_b32 s8, s4, 6
	s_lshl_b32 s9, s4, 4
	s_mov_b64 s[4:5], 0
	s_branch .LBB0_115
.LBB0_114:
	s_or_b64 exec, exec, s[6:7]
	s_load_dwordx2 s[6:7], s[0:1], 0xa8
	v_lshlrev_b32_e32 v6, 5, v2
	v_and_b32_e32 v112, 0xe0, v6
	v_lshl_add_u64 v[0:1], v[0:1], 0, v[112:113]
	v_lshlrev_b32_e32 v112, 10, v3
	s_waitcnt lgkmcnt(0)
	v_mov_b64_e32 v[6:7], s[6:7]
	s_movk_i32 s6, 0x1c00
	v_mad_i64_i32 v[6:7], s[6:7], v5, s6, v[6:7]
	v_lshl_add_u64 v[6:7], v[6:7], 0, v[112:113]
	v_lshlrev_b32_e32 v112, 4, v4
	v_lshl_add_u64 v[4:5], v[6:7], 0, v[112:113]
	s_mov_b32 s6, 0x6000000
	v_add_co_u32_e32 v4, vcc, s6, v4
	s_mov_b32 s6, s54
	s_nop 0
	v_addc_co_u32_e32 v5, vcc, 0, v5, vcc
	global_load_dwordx4 v[4:7], v[4:5], off offset:1024
	s_waitcnt vmcnt(0)
	v_lshlrev_b32_e32 v8, 16, v4
	v_and_b32_e32 v9, 0xffff0000, v4
	v_lshlrev_b32_e32 v10, 16, v5
	v_and_b32_e32 v11, 0xffff0000, v5
	v_lshlrev_b32_e32 v4, 16, v6
	v_and_b32_e32 v5, 0xffff0000, v6
	v_lshlrev_b32_e32 v6, 16, v7
	v_and_b32_e32 v7, 0xffff0000, v7
	global_store_dwordx4 v[0:1], v[8:11], off nt
	global_store_dwordx4 v[0:1], v[4:7], off offset:16 nt
	s_nop 0
	v_add_u32_e32 v2, s38, v2
	s_movk_i32 s38, 0x200
	v_cmp_lt_i32_e32 vcc, s39, v2
	s_or_b64 s[4:5], vcc, s[4:5]
	s_andn2_b64 exec, exec, s[4:5]
	s_cbranch_execz .LBB0_120
